# NSA compressed pass 1: hand-written unmasked body for fully valid key blocks (diagonal blocks keep the masked body)
# speedup vs baseline: 1.0240x; 1.0034x over previous
.LBB0_1064:
	s_and_b32 s6, s25, 15
	s_cmp_eq_u32 s6, 0
	s_cselect_b32 s6, 1, 0
	s_sub_i32 s6, s36, s6
	s_cmp_lt_i32 s37, s6
	s_cbranch_scc1 .Lp1_fast
	s_add_i32 s6, s38, 0
	v_add_u32_e32 v29, s6, v163
	ds_read_b128 v[30:33], v29
	ds_read_b128 v[34:37], v29 offset:4096
	v_add_u32_e32 v29, s6, v165
	v_add_u32_e32 v66, s6, v211
	ds_read_b128 v[46:49], v29 offset:4096
	ds_read_b128 v[50:53], v29
	s_waitcnt vmcnt(3) lgkmcnt(2)
	v_mfma_f32_16x16x32_bf16 v[42:45], v[34:37], v[14:17], 0
	ds_read_b128 v[58:61], v66 offset:4096
	ds_read_b128 v[66:69], v66
	v_add_u32_e32 v29, s6, v212
	v_add_u32_e32 v81, v0, v19
	s_waitcnt vmcnt(1)
	v_mfma_f32_16x16x32_bf16 v[34:37], v[34:37], v[10:13], 0
	v_cmp_lt_i32_e32 vcc, 31, v81
	ds_read_b128 v[70:73], v29
	s_add_i32 s6, s38, 0x4000
	s_waitcnt lgkmcnt(2)
	v_mfma_f32_16x16x32_bf16 v[42:45], v[58:61], v[2:5], v[42:45]
	s_cmpk_lg_u32 s38, 0x8000
	s_cselect_b32 s38, s6, 0
	s_add_i32 s6, s12, 0x4000
	s_waitcnt vmcnt(0)
	v_mfma_f32_16x16x32_bf16 v[34:37], v[58:61], v[6:9], v[34:37]
	ds_read_b128 v[58:61], v29 offset:4096
	s_nop 1
	v_cndmask_b32_e32 v82, v201, v42, vcc
	v_cmp_lt_i32_e32 vcc, 32, v81
	v_mfma_f32_16x16x32_bf16 v[54:57], v[46:49], v[14:17], 0
	v_add_u32_e32 v29, v0, v18
	v_cndmask_b32_e32 v83, v201, v43, vcc
	v_cmp_lt_i32_e32 vcc, 33, v81
	v_mfma_f32_16x16x32_bf16 v[46:49], v[46:49], v[10:13], 0
	s_cmpk_lg_u32 s12, 0x8000
	v_cndmask_b32_e32 v84, v201, v44, vcc
	v_cmp_lt_i32_e32 vcc, 34, v29
	s_waitcnt lgkmcnt(0)
	v_mfma_f32_16x16x32_bf16 v[46:49], v[58:61], v[6:9], v[46:49]
	s_cselect_b32 s12, s6, 0
	v_cndmask_b32_e32 v85, v201, v37, vcc
	v_cmp_lt_i32_e32 vcc, 34, v81
	v_mfma_f32_16x16x32_bf16 v[54:57], v[58:61], v[2:5], v[54:57]
	s_add_i32 s6, s37, 1
	v_cndmask_b32_e32 v86, v201, v45, vcc
	v_cmp_lt_i32_e32 vcc, 35, v29
	v_mfma_f32_16x16x32_bf16 v[58:61], v[50:53], v[14:17], 0
	v_subrev_u32_e32 v0, 64, v0
	v_cndmask_b32_e32 v87, v201, v46, vcc
	v_cmp_lt_i32_e32 vcc, 35, v81
	v_mfma_f32_16x16x32_bf16 v[38:41], v[30:33], v[14:17], 0
	v_lshl_add_u64 v[24:25], v[24:25], 0, s[80:81]
	v_cndmask_b32_e32 v54, v201, v54, vcc
	v_cmp_lt_i32_e32 vcc, 36, v29
	v_mfma_f32_16x16x32_bf16 v[30:33], v[30:33], v[10:13], 0
	s_cmp_lg_u32 s37, s36
	v_cndmask_b32_e32 v88, v201, v47, vcc
	v_cmp_lt_i32_e32 vcc, 36, v81
	v_mfma_f32_16x16x32_bf16 v[42:45], v[70:73], v[2:5], v[58:61]
	v_add_u32_e32 v26, 64, v26
	v_cndmask_b32_e32 v55, v201, v55, vcc
	v_cmp_lt_i32_e32 vcc, 37, v29
	v_mfma_f32_16x16x32_bf16 v[30:33], v[66:69], v[6:9], v[30:33]
	s_nop 0
	v_cndmask_b32_e32 v58, v201, v48, vcc
	v_cmp_lt_i32_e32 vcc, 37, v81
	v_mfma_f32_16x16x32_bf16 v[38:41], v[66:69], v[2:5], v[38:41]
	s_nop 0
	v_cndmask_b32_e32 v56, v201, v56, vcc
	v_cmp_lt_i32_e32 vcc, 38, v29
	s_nop 1
	v_cndmask_b32_e32 v59, v201, v49, vcc
	v_cmp_lt_i32_e32 vcc, 38, v81
	v_mfma_f32_16x16x32_bf16 v[46:49], v[50:53], v[10:13], 0
	s_nop 0
	v_cndmask_b32_e32 v57, v201, v57, vcc
	v_cmp_lt_i32_e32 vcc, 31, v29
	s_nop 1
	v_cndmask_b32_e32 v60, v201, v34, vcc
	v_cmp_lt_i32_e32 vcc, 32, v29
	s_nop 1
	v_cndmask_b32_e32 v50, v201, v35, vcc
	v_cmp_lt_i32_e32 vcc, 33, v29
	s_nop 1
	v_cndmask_b32_e32 v51, v201, v36, vcc
	v_cmp_lt_i32_e32 vcc, -1, v29
	v_mfma_f32_16x16x32_bf16 v[34:37], v[70:73], v[6:9], v[46:49]
	s_nop 0
	v_cndmask_b32_e32 v30, v201, v30, vcc
	v_cmp_lt_i32_e32 vcc, -1, v81
	s_nop 1
	v_cndmask_b32_e32 v38, v201, v38, vcc
	v_cmp_lt_i32_e32 vcc, 0, v29
	s_nop 1
	v_cndmask_b32_e32 v46, v201, v31, vcc
	v_cmp_lt_i32_e32 vcc, 0, v81
	s_nop 1
	v_cndmask_b32_e32 v39, v201, v39, vcc
	v_cmp_lt_i32_e32 vcc, 1, v29
	v_max3_f32 v31, v38, s83, v39
	s_nop 0
	v_cndmask_b32_e32 v32, v201, v32, vcc
	v_cmp_lt_i32_e32 vcc, 1, v81
	s_nop 1
	v_cndmask_b32_e32 v40, v201, v40, vcc
	v_cmp_lt_i32_e32 vcc, 2, v29
	s_nop 1
	v_cndmask_b32_e32 v47, v201, v33, vcc
	v_cmp_lt_i32_e32 vcc, 2, v81
	s_nop 1
	v_cndmask_b32_e32 v41, v201, v41, vcc
	v_cmp_lt_i32_e32 vcc, 3, v29
	v_max3_f32 v31, v31, v40, v41
	s_nop 0
	v_cndmask_b32_e32 v48, v201, v34, vcc
	v_cmp_lt_i32_e32 vcc, 3, v81
	s_nop 1
	v_cndmask_b32_e32 v42, v201, v42, vcc
	v_cmp_lt_i32_e32 vcc, 4, v29
	s_nop 1
	v_cndmask_b32_e32 v49, v201, v35, vcc
	v_cmp_lt_i32_e32 vcc, 4, v81
	s_nop 1
	v_cndmask_b32_e32 v43, v201, v43, vcc
	v_cmp_lt_i32_e32 vcc, 5, v29
	v_max3_f32 v31, v31, v42, v43
	s_nop 0
	v_cndmask_b32_e32 v36, v201, v36, vcc
	v_cmp_lt_i32_e32 vcc, 5, v81
	s_nop 1
	v_cndmask_b32_e32 v44, v201, v44, vcc
	v_cmp_lt_i32_e32 vcc, 6, v29
	s_nop 1
	v_cndmask_b32_e32 v37, v201, v37, vcc
	v_cmp_lt_i32_e32 vcc, 6, v81
	s_nop 1
	v_cndmask_b32_e32 v45, v201, v45, vcc
	v_max3_f32 v29, v31, v44, v45
	v_max3_f32 v29, v29, v82, v83
	v_max3_f32 v29, v29, v84, v86
	v_max3_f32 v29, v29, v54, v55
	v_max3_f32 v29, v29, v56, v57
	v_mov_b32_e32 v31, v29
	s_nop 1
	v_permlane16_swap_b32_e32 v29, v31
	v_max_f32_e32 v31, v31, v31
	v_max_f32_e32 v29, v29, v29
	v_max_f32_e32 v29, v29, v31
	v_mov_b32_e32 v31, v29
	s_nop 1
	v_permlane32_swap_b32_e32 v29, v31
	v_max3_f32 v81, v28, v29, v31
	v_sub_f32_e32 v33, v28, v81
	v_sub_f32_e32 v28, v38, v81
	v_exp_f32_e32 v29, v28
	v_sub_f32_e32 v28, v39, v81
	v_exp_f32_e32 v34, v28
	v_sub_f32_e32 v28, v40, v81
	v_exp_f32_e32 v52, v28
	v_sub_f32_e32 v28, v41, v81
	v_exp_f32_e32 v53, v28
	v_sub_f32_e32 v28, v42, v81
	v_exp_f32_e32 v61, v28
	v_sub_f32_e32 v28, v43, v81
	v_exp_f32_e32 v66, v28
	v_sub_f32_e32 v28, v44, v81
	v_exp_f32_e32 v67, v28
	v_sub_f32_e32 v28, v82, v81
	v_exp_f32_e32 v28, v28
	v_sub_f32_e32 v31, v45, v81
	v_cmp_lt_f32_e32 vcc, s76, v82
	v_exp_f32_e32 v68, v31
	v_sub_f32_e32 v35, v57, v81
	v_cndmask_b32_e32 v31, 0, v28, vcc
	v_sub_f32_e32 v28, v83, v81
	v_exp_f32_e32 v69, v28
	v_sub_f32_e32 v28, v84, v81
	v_exp_f32_e32 v70, v28
	v_sub_f32_e32 v28, v86, v81
	v_exp_f32_e32 v71, v28
	v_sub_f32_e32 v28, v54, v81
	v_exp_f32_e32 v72, v28
	v_sub_f32_e32 v28, v55, v81
	v_exp_f32_e32 v73, v28
	v_sub_f32_e32 v28, v56, v81
	v_exp_f32_e32 v89, v28
	v_max3_f32 v28, v30, s83, v46
	v_max3_f32 v28, v28, v32, v47
	v_max3_f32 v28, v28, v48, v49
	v_max3_f32 v28, v28, v36, v37
	v_max3_f32 v28, v28, v60, v50
	v_max3_f32 v28, v28, v51, v85
	v_max3_f32 v28, v28, v87, v88
	v_max3_f32 v28, v28, v58, v59
	v_mov_b32_e32 v82, v28
	s_nop 1
	v_permlane16_swap_b32_e32 v28, v82
	v_max_f32_e32 v82, v82, v82
	v_max_f32_e32 v28, v28, v28
	v_max_f32_e32 v28, v28, v82
	v_mov_b32_e32 v82, v28
	s_nop 1
	v_permlane32_swap_b32_e32 v28, v82
	v_max3_f32 v82, v27, v28, v82
	v_sub_f32_e32 v28, v30, v82
	v_exp_f32_e32 v28, v28
	v_cmp_lt_f32_e32 vcc, s76, v38
	v_exp_f32_e32 v90, v35
	v_sub_f32_e32 v27, v27, v82
	v_pk_add_f32 v[28:29], v[28:29], 0 op_sel_hi:[1,0]
	v_exp_f32_e32 v33, v33
	v_cndmask_b32_e32 v29, 0, v29, vcc
	v_cmp_lt_f32_e32 vcc, s76, v30
	v_sub_f32_e32 v30, v46, v82
	v_exp_f32_e32 v30, v30
	v_cndmask_b32_e32 v28, 0, v28, vcc
	v_cmp_lt_f32_e32 vcc, s76, v39
	s_nop 1
	v_cndmask_b32_e32 v35, 0, v34, vcc
	v_cmp_lt_f32_e32 vcc, s76, v46
	s_nop 1
	v_cndmask_b32_e32 v34, 0, v30, vcc
	v_sub_f32_e32 v30, v32, v82
	v_exp_f32_e32 v30, v30
	v_cmp_lt_f32_e32 vcc, s76, v40
	v_pk_add_f32 v[28:29], v[34:35], v[28:29]
	s_nop 0
	v_cndmask_b32_e32 v35, 0, v52, vcc
	v_cmp_lt_f32_e32 vcc, s76, v32
	v_sub_f32_e32 v32, v60, v82
	v_exp_f32_e32 v32, v32
	v_cndmask_b32_e32 v34, 0, v30, vcc
	v_sub_f32_e32 v30, v47, v82
	v_exp_f32_e32 v30, v30
	v_cmp_lt_f32_e32 vcc, s76, v41
	v_pk_add_f32 v[28:29], v[34:35], v[28:29]
	s_nop 0
	v_cndmask_b32_e32 v35, 0, v53, vcc
	v_cmp_lt_f32_e32 vcc, s76, v47
	s_nop 1
	v_cndmask_b32_e32 v34, 0, v30, vcc
	v_sub_f32_e32 v30, v48, v82
	v_exp_f32_e32 v30, v30
	v_cmp_lt_f32_e32 vcc, s76, v42
	v_pk_add_f32 v[28:29], v[34:35], v[28:29]
	s_nop 0
	v_cndmask_b32_e32 v35, 0, v61, vcc
	v_cmp_lt_f32_e32 vcc, s76, v48
	s_nop 1
	v_cndmask_b32_e32 v34, 0, v30, vcc
	v_sub_f32_e32 v30, v49, v82
	v_exp_f32_e32 v30, v30
	v_cmp_lt_f32_e32 vcc, s76, v43
	v_pk_add_f32 v[28:29], v[34:35], v[28:29]
	s_nop 0
	v_cndmask_b32_e32 v35, 0, v66, vcc
	v_cmp_lt_f32_e32 vcc, s76, v49
	s_nop 1
	v_cndmask_b32_e32 v34, 0, v30, vcc
	v_sub_f32_e32 v30, v36, v82
	v_exp_f32_e32 v30, v30
	v_cmp_lt_f32_e32 vcc, s76, v44
	v_pk_add_f32 v[28:29], v[34:35], v[28:29]
	s_nop 0
	v_cndmask_b32_e32 v35, 0, v67, vcc
	v_cmp_lt_f32_e32 vcc, s76, v36
	s_nop 1
	v_cndmask_b32_e32 v34, 0, v30, vcc
	v_sub_f32_e32 v30, v37, v82
	v_exp_f32_e32 v30, v30
	v_cmp_lt_f32_e32 vcc, s76, v45
	v_pk_add_f32 v[28:29], v[34:35], v[28:29]
	s_nop 0
	v_cndmask_b32_e32 v35, 0, v68, vcc
	v_cmp_lt_f32_e32 vcc, s76, v37
	s_nop 1
	v_cndmask_b32_e32 v34, 0, v30, vcc
	v_cmp_lt_f32_e32 vcc, s76, v60
	v_pk_add_f32 v[28:29], v[34:35], v[28:29]
	s_nop 0
	v_cndmask_b32_e32 v30, 0, v32, vcc
	v_pk_add_f32 v[28:29], v[30:31], v[28:29]
	v_sub_f32_e32 v30, v50, v82
	v_exp_f32_e32 v30, v30
	v_cmp_lt_f32_e32 vcc, s76, v83
	v_exp_f32_e32 v32, v27
	s_nop 0
	v_cndmask_b32_e32 v31, 0, v69, vcc
	v_cmp_lt_f32_e32 vcc, s76, v50
	s_nop 1
	v_cndmask_b32_e32 v30, 0, v30, vcc
	v_pk_add_f32 v[28:29], v[30:31], v[28:29]
	v_sub_f32_e32 v30, v51, v82
	v_exp_f32_e32 v30, v30
	v_cmp_lt_f32_e32 vcc, s76, v84
	s_nop 1
	v_cndmask_b32_e32 v31, 0, v70, vcc
	v_cmp_lt_f32_e32 vcc, s76, v51
	s_nop 1
	v_cndmask_b32_e32 v30, 0, v30, vcc
	v_pk_add_f32 v[28:29], v[30:31], v[28:29]
	v_sub_f32_e32 v30, v85, v82
	v_exp_f32_e32 v30, v30
	v_cmp_lt_f32_e32 vcc, s76, v86
	s_nop 1
	v_cndmask_b32_e32 v31, 0, v71, vcc
	v_cmp_lt_f32_e32 vcc, s76, v85
	s_nop 1
	v_cndmask_b32_e32 v30, 0, v30, vcc
	v_pk_add_f32 v[28:29], v[30:31], v[28:29]
	v_sub_f32_e32 v30, v87, v82
	v_exp_f32_e32 v30, v30
	v_cmp_lt_f32_e32 vcc, s76, v54
	s_nop 1
	v_cndmask_b32_e32 v31, 0, v72, vcc
	v_cmp_lt_f32_e32 vcc, s76, v87
	s_nop 1
	v_cndmask_b32_e32 v30, 0, v30, vcc
	v_pk_add_f32 v[28:29], v[30:31], v[28:29]
	v_sub_f32_e32 v30, v88, v82
	v_exp_f32_e32 v30, v30
	v_cmp_lt_f32_e32 vcc, s76, v55
	s_nop 1
	v_cndmask_b32_e32 v31, 0, v73, vcc
	v_cmp_lt_f32_e32 vcc, s76, v88
	s_nop 1
	v_cndmask_b32_e32 v30, 0, v30, vcc
	v_pk_add_f32 v[28:29], v[30:31], v[28:29]
	v_sub_f32_e32 v30, v58, v82
	v_exp_f32_e32 v30, v30
	v_cmp_lt_f32_e32 vcc, s76, v56
	s_nop 1
	v_cndmask_b32_e32 v31, 0, v89, vcc
	v_cmp_lt_f32_e32 vcc, s76, v58
	s_nop 1
	v_cndmask_b32_e32 v30, 0, v30, vcc
	v_pk_add_f32 v[28:29], v[30:31], v[28:29]
	v_sub_f32_e32 v30, v59, v82
	v_exp_f32_e32 v30, v30
	v_cmp_lt_f32_e32 vcc, s76, v57
	s_nop 1
	v_cndmask_b32_e32 v31, 0, v90, vcc
	v_cmp_lt_f32_e32 vcc, s76, v59
	s_nop 1
	v_cndmask_b32_e32 v30, 0, v30, vcc
	v_pk_add_f32 v[28:29], v[30:31], v[28:29]
	s_nop 0
	v_pk_fma_f32 v[20:21], v[20:21], v[32:33], v[28:29]
	s_cbranch_scc0 .LBB0_1068
	v_mov_b32_e32 v28, v81
	v_mov_b32_e32 v27, v82
	s_mov_b32 s37, s6
	s_cmp_ge_u32 s37, s36
	s_mov_b64 s[6:7], -1
	s_cbranch_scc1 .LBB0_1061

.Lp1_fast:
	s_add_i32 s6, s38, 0
	v_add_u32_e32 v29, s6, v163
	ds_read_b128 v[30:33], v29
	ds_read_b128 v[34:37], v29 offset:4096
	v_add_u32_e32 v81, s6, v211
	ds_read_b128 v[66:69], v81
	ds_read_b128 v[58:61], v81 offset:4096
	v_add_u32_e32 v29, s6, v165
	ds_read_b128 v[50:53], v29
	ds_read_b128 v[46:49], v29 offset:4096
	v_add_u32_e32 v81, s6, v212
	ds_read_b128 v[70:73], v81
	ds_read_b128 v[86:89], v81 offset:4096
	s_add_i32 s6, s38, 0x4000
	s_cmpk_lg_u32 s38, 0x8000
	s_cselect_b32 s38, s6, 0
	s_add_i32 s6, s12, 0x4000
	s_cmpk_lg_u32 s12, 0x8000
	s_cselect_b32 s12, s6, 0
	v_subrev_u32_e32 v0, 64, v0
	v_lshl_add_u64 v[24:25], v[24:25], 0, s[80:81]
	v_add_u32_e32 v26, 64, v26
	s_waitcnt lgkmcnt(6)
	v_mfma_f32_16x16x32_bf16 v[38:41], v[30:33], v[14:17], 0
	v_mfma_f32_16x16x32_bf16 v[42:45], v[34:37], v[14:17], 0
	v_mfma_f32_16x16x32_bf16 v[30:33], v[30:33], v[10:13], 0
	v_mfma_f32_16x16x32_bf16 v[34:37], v[34:37], v[10:13], 0
	s_waitcnt lgkmcnt(4)
	v_mfma_f32_16x16x32_bf16 v[38:41], v[66:69], v[2:5], v[38:41]
	v_mfma_f32_16x16x32_bf16 v[42:45], v[58:61], v[2:5], v[42:45]
	v_mfma_f32_16x16x32_bf16 v[30:33], v[66:69], v[6:9], v[30:33]
	v_mfma_f32_16x16x32_bf16 v[34:37], v[58:61], v[6:9], v[34:37]
	s_waitcnt lgkmcnt(2)
	v_mfma_f32_16x16x32_bf16 v[54:57], v[50:53], v[14:17], 0
	v_mfma_f32_16x16x32_bf16 v[82:85], v[46:49], v[14:17], 0
	v_mfma_f32_16x16x32_bf16 v[50:53], v[50:53], v[10:13], 0
	v_mfma_f32_16x16x32_bf16 v[46:49], v[46:49], v[10:13], 0
	s_waitcnt lgkmcnt(0)
	v_mfma_f32_16x16x32_bf16 v[54:57], v[70:73], v[2:5], v[54:57]
	v_mfma_f32_16x16x32_bf16 v[82:85], v[86:89], v[2:5], v[82:85]
	v_mfma_f32_16x16x32_bf16 v[50:53], v[70:73], v[6:9], v[50:53]
	v_mfma_f32_16x16x32_bf16 v[46:49], v[86:89], v[6:9], v[46:49]
	v_max3_f32 v29, v38, v39, v40
	v_max3_f32 v81, v41, v42, v43
	v_max3_f32 v29, v29, v44, v45
	s_nop 1
	v_max3_f32 v81, v81, v54, v55
	v_max3_f32 v29, v29, v56, v57
	v_max3_f32 v81, v81, v82, v83
	v_max3_f32 v29, v29, v84, v85
	v_max_f32_e32 v29, v29, v81
	v_mov_b32_e32 v81, v29
	s_nop 1
	v_permlane16_swap_b32_e32 v29, v81
	v_max_f32_e32 v29, v29, v81
	v_mov_b32_e32 v81, v29
	s_nop 1
	v_permlane32_swap_b32_e32 v29, v81
	v_max3_f32 v81, v28, v29, v81
	v_sub_f32_e32 v90, v28, v81
	v_exp_f32_e32 v90, v90
	v_sub_f32_e32 v38, v38, v81
	v_sub_f32_e32 v39, v39, v81
	v_sub_f32_e32 v40, v40, v81
	v_sub_f32_e32 v41, v41, v81
	v_sub_f32_e32 v54, v54, v81
	v_sub_f32_e32 v55, v55, v81
	v_sub_f32_e32 v56, v56, v81
	v_sub_f32_e32 v57, v57, v81
	v_sub_f32_e32 v42, v42, v81
	v_sub_f32_e32 v43, v43, v81
	v_sub_f32_e32 v44, v44, v81
	v_sub_f32_e32 v45, v45, v81
	v_sub_f32_e32 v82, v82, v81
	v_sub_f32_e32 v83, v83, v81
	v_sub_f32_e32 v84, v84, v81
	v_sub_f32_e32 v85, v85, v81
	v_exp_f32_e32 v38, v38
	v_exp_f32_e32 v39, v39
	v_exp_f32_e32 v40, v40
	v_exp_f32_e32 v41, v41
	v_exp_f32_e32 v54, v54
	v_exp_f32_e32 v55, v55
	v_exp_f32_e32 v56, v56
	v_exp_f32_e32 v57, v57
	v_exp_f32_e32 v42, v42
	v_exp_f32_e32 v43, v43
	v_exp_f32_e32 v44, v44
	v_exp_f32_e32 v45, v45
	v_exp_f32_e32 v82, v82
	v_exp_f32_e32 v83, v83
	v_exp_f32_e32 v84, v84
	v_exp_f32_e32 v85, v85
	v_add_f32_e32 v29, v38, v39
	v_add_f32_e32 v29, v29, v40
	v_add_f32_e32 v29, v29, v41
	v_add_f32_e32 v29, v29, v54
	v_add_f32_e32 v29, v29, v55
	v_add_f32_e32 v29, v29, v56
	v_add_f32_e32 v29, v29, v57
	v_add_f32_e32 v29, v29, v42
	v_add_f32_e32 v29, v29, v43
	v_add_f32_e32 v29, v29, v44
	v_add_f32_e32 v29, v29, v45
	v_add_f32_e32 v29, v29, v82
	v_add_f32_e32 v29, v29, v83
	v_add_f32_e32 v29, v29, v84
	v_add_f32_e32 v29, v29, v85
	v_fma_f32 v21, v21, v90, v29
	v_mov_b32_e32 v28, v81
	v_max3_f32 v58, v30, v31, v32
	v_max3_f32 v59, v33, v50, v51
	v_max3_f32 v58, v58, v52, v53
	s_nop 1
	v_max3_f32 v59, v59, v34, v35
	v_max3_f32 v58, v58, v36, v37
	v_max3_f32 v59, v59, v46, v47
	v_max3_f32 v58, v58, v48, v49
	v_max_f32_e32 v58, v58, v59
	v_mov_b32_e32 v59, v58
	s_nop 1
	v_permlane16_swap_b32_e32 v58, v59
	v_max_f32_e32 v58, v58, v59
	v_mov_b32_e32 v59, v58
	s_nop 1
	v_permlane32_swap_b32_e32 v58, v59
	v_max3_f32 v59, v27, v58, v59
	v_sub_f32_e32 v60, v27, v59
	v_exp_f32_e32 v60, v60
	v_sub_f32_e32 v30, v30, v59
	v_sub_f32_e32 v31, v31, v59
	v_sub_f32_e32 v32, v32, v59
	v_sub_f32_e32 v33, v33, v59
	v_sub_f32_e32 v50, v50, v59
	v_sub_f32_e32 v51, v51, v59
	v_sub_f32_e32 v52, v52, v59
	v_sub_f32_e32 v53, v53, v59
	v_sub_f32_e32 v34, v34, v59
	v_sub_f32_e32 v35, v35, v59
	v_sub_f32_e32 v36, v36, v59
	v_sub_f32_e32 v37, v37, v59
	v_sub_f32_e32 v46, v46, v59
	v_sub_f32_e32 v47, v47, v59
	v_sub_f32_e32 v48, v48, v59
	v_sub_f32_e32 v49, v49, v59
	v_exp_f32_e32 v30, v30
	v_exp_f32_e32 v31, v31
	v_exp_f32_e32 v32, v32
	v_exp_f32_e32 v33, v33
	v_exp_f32_e32 v50, v50
	v_exp_f32_e32 v51, v51
	v_exp_f32_e32 v52, v52
	v_exp_f32_e32 v53, v53
	v_exp_f32_e32 v34, v34
	v_exp_f32_e32 v35, v35
	v_exp_f32_e32 v36, v36
	v_exp_f32_e32 v37, v37
	v_exp_f32_e32 v46, v46
	v_exp_f32_e32 v47, v47
	v_exp_f32_e32 v48, v48
	v_exp_f32_e32 v49, v49
	v_add_f32_e32 v58, v30, v31
	v_add_f32_e32 v58, v58, v32
	v_add_f32_e32 v58, v58, v33
	v_add_f32_e32 v58, v58, v50
	v_add_f32_e32 v58, v58, v51
	v_add_f32_e32 v58, v58, v52
	v_add_f32_e32 v58, v58, v53
	v_add_f32_e32 v58, v58, v34
	v_add_f32_e32 v58, v58, v35
	v_add_f32_e32 v58, v58, v36
	v_add_f32_e32 v58, v58, v37
	v_add_f32_e32 v58, v58, v46
	v_add_f32_e32 v58, v58, v47
	v_add_f32_e32 v58, v58, v48
	v_add_f32_e32 v58, v58, v49
	v_fma_f32 v20, v20, v60, v58
	v_mov_b32_e32 v27, v59
	s_add_i32 s37, s37, 1
	s_cmp_ge_u32 s37, s36
	s_mov_b64 s[6:7], -1
	s_cbranch_scc1 .LBB0_1061
	s_branch .LBB0_1066
